# P1 K-loop load segments rewritten VALU-free (LDS-DMA in scalar-base form, A-fragment ds_reads from one base register), on top of team stagger + aligned P3 hook
# speedup vs baseline: 1.0095x; 1.0035x over previous
.LBB0_172:
	s_add_u32 s4, s50, 0x4000000
	s_addc_u32 s5, s51, 0
	s_add_u32 s6, s50, 0x4800000
	v_readlane_b32 s8, v245, 9
	s_addc_u32 s7, s51, 0
	s_lshl_b32 s8, s8, 2
	s_add_u32 s8, s70, s8
	s_addc_u32 s9, s71, 0
	s_add_u32 s8, s8, 0xa0000
	s_addc_u32 s9, s9, 0
	s_lshl_b32 s10, s10, 5
	s_and_b32 s19, s10, 0x60
	s_mov_b64 s[10:11], 0x80
	s_add_i32 m0, s43, 0x18000
	v_lshl_add_u64 v[8:9], v[8:9], 0, s[10:11]
	s_lshl_b32 s13, s18, 13
	s_lshl_b32 s22, s19, 7
	s_waitcnt vmcnt(2)
	s_barrier
	global_load_lds_dwordx4 v[8:9], off
	v_lshl_add_u64 v[6:7], v[6:7], 0, s[10:11]
	s_add_i32 m0, s43, 0x1a000
	s_add_i32 s57, s43, 0x8000
	s_add_i32 s58, s43, 0xa000
	global_load_lds_dwordx4 v[6:7], off
	v_lshl_add_u64 v[2:3], v[2:3], 0, s[10:11]
	s_mov_b32 m0, s57
	s_add_u32 s20, s44, 0x40080
	global_load_lds_dwordx4 v[2:3], off
	v_lshl_add_u64 v[2:3], v[4:5], 0, s[10:11]
	s_mov_b32 m0, s58
	s_addc_u32 s21, s45, 0
	global_load_lds_dwordx4 v[2:3], off
	s_add_i32 m0, s43, 0x1c000
	v_lshl_add_u64 v[2:3], s[20:21], 0, v[140:141]
	global_load_lds_dwordx4 v[2:3], off
	v_lshl_add_u64 v[2:3], s[20:21], 0, v[144:145]
	s_add_i32 m0, s43, 0x1e000
	s_cmpk_lt_u32 s12, 0x100
	global_load_lds_dwordx4 v[2:3], off
	v_lshrrev_b32_e32 v3, 1, v10
	v_and_b32_e32 v3, 24, v3
	v_and_b32_e32 v2, 15, v10
	v_lshlrev_b32_e32 v4, 1, v3
	v_lshl_or_b32 v170, s18, 6, v2
	v_lshl_or_b32 v4, v2, 6, v4
	v_lshlrev_b32_e32 v2, 2, v2
	v_and_b32_e32 v5, 32, v2
	v_bitop3_b32 v6, v4, s13, v5 bitop3:0xde
	s_cselect_b64 s[12:13], -1, 0
	s_lshl_b32 s18, s18, 8
	s_add_i32 s18, s18, 0
	s_add_i32 s18, s18, 0x20400
	v_add_u32_e32 v175, s18, v2
	v_lshlrev_b32_e32 v2, 14, v11
	v_and_b32_e32 v2, 0xffff8000, v2
	v_or_b32_e32 v173, s19, v3
	v_lshl_add_u32 v2, v12, 11, v2
	v_and_b32_e32 v3, 1, v11
	v_lshl_or_b32 v2, v3, 6, v2
	v_lshl_add_u32 v146, v13, 1, v2
	v_lshlrev_b32_e32 v2, 14, v14
	v_and_b32_e32 v2, 0xffff8000, v2
	v_lshl_add_u32 v2, v15, 11, v2
	v_and_b32_e32 v3, 1, v14
	s_mov_b64 s[20:21], 0x40080
	s_waitcnt vmcnt(6)
	v_readlane_b32 s18, v245, 0
	v_lshl_or_b32 v2, v3, 6, v2
	s_bitcmp1_b32 s18, 0
	v_lshl_add_u64 v[148:149], v[146:147], 0, s[20:21]
	v_lshl_add_u32 v146, v16, 1, v2
	s_mov_b32 s59, 0
	v_bitop3_b32 v171, v4, s22, v5 bitop3:0xde
	v_add_u32_e32 v240, 0x10000, v171
	v_and_b32_e32 v172, 63, v0
	v_or_b32_e32 v174, 0xfffffc00, v173
	s_cselect_b64 s[18:19], -1, 0
	v_lshl_add_u64 v[150:151], v[146:147], 0, s[20:21]
	s_add_i32 s60, 0, 0x10000
	s_add_i32 s61, 0, 0x14000
	v_add_u32_e32 v176, 0, v6
	s_mov_b64 s[20:21], 0x20000
	s_mov_b64 s[22:23], 0x24000
	s_mov_b64 s[24:25], 0x28000
	s_mov_b64 s[26:27], 0x2c000
	v_mov_b64_e32 v[152:153], 0x40000
	v_mov_b64_e32 v[154:155], 0x48000
	v_mov_b64_e32 v[156:157], 0x50000
	v_mov_b64_e32 v[158:159], 0x58000
	v_mov_b32_e32 v177, 0x3e38aa3b
	s_barrier
	s_branch .LBB0_175

.LBB0_177:
	s_ashr_i32 s29, s28, 31
	s_lshl_b64 s[38:39], s[28:29], 19
	s_add_u32 s38, s84, s38
	s_addc_u32 s39, s85, s39
	s_and_b64 s[40:41], s[36:37], exec
	s_cselect_b32 s29, s39, s1
	s_cselect_b32 s62, s38, s0
	s_ashr_i32 s35, s34, 31
	s_lshl_b64 s[40:41], s[34:35], 19
	s_add_u32 s40, s16, s40
	s_addc_u32 s41, s17, s41
	s_and_b64 s[46:47], s[36:37], exec
	s_cselect_b32 s63, s41, s45
	s_cselect_b32 s64, s40, s44
	s_lshl_b32 s35, s30, 8
	s_add_u32 s65, s44, 0x100
	v_mov_b32_e32 v2, 0
	v_or_b32_e32 v134, s35, v172
	v_lshl_add_u64 v[130:131], s[0:1], 0, v[148:149]
	v_lshl_add_u64 v[132:133], s[0:1], 0, v[150:151]
	s_addc_u32 s66, s45, 0
	s_mov_b32 s67, -2
	s_mov_b64 s[30:31], 0
	s_waitcnt lgkmcnt(0)
	ds_read_b128 v[160:163], v240
	ds_read_b128 v[164:167], v240 offset:1024
	ds_read_b128 v[178:181], v240 offset:2048
	ds_read_b128 v[182:185], v240 offset:3072
	s_add_u32 s44, s0, s30
	ds_read_b128 v[186:189], v240 offset:16384
	ds_read_b128 v[190:193], v240 offset:17408
	ds_read_b128 v[194:197], v240 offset:18432
	ds_read_b128 v[198:201], v240 offset:19456
	s_addc_u32 s45, s1, s31
	s_add_u32 s44, s44, 0x100
	s_addc_u32 s45, s45, 0
	s_add_u32 s72, s65, s30
	s_addc_u32 s73, s66, s31
	s_cmpk_eq_i32 s30, 0x700
	s_cselect_b32 s47, s29, s45
	s_cselect_b32 s46, s62, s44
	s_cselect_b32 s45, s63, s73
	s_cselect_b32 s44, s64, s72
	s_add_u32 s90, s0, s30
	s_addc_u32 s91, s1, s31
	s_add_i32 m0, s43, 0xc000
	ds_read_b128 v[202:205], v176
	ds_read_b128 v[206:209], v176 offset:1024
	ds_read_b128 v[210:213], v176 offset:2048
	ds_read_b128 v[214:217], v176 offset:3072
	ds_read_b128 v[218:221], v176 offset:4096
	ds_read_b128 v[222:225], v176 offset:5120
	ds_read_b128 v[226:229], v176 offset:6144
	ds_read_b128 v[230:233], v176 offset:7168
	global_load_lds_dwordx4 v148, s[90:91]
	s_add_i32 m0, s43, 0xe000
	s_nop 0
	global_load_lds_dwordx4 v150, s[90:91]
	s_waitcnt vmcnt(8)
	s_waitcnt lgkmcnt(0)
	s_barrier
	s_setprio 1
	v_mfma_f32_16x16x32_bf16 v[126:129], v[160:163], v[202:205], 0
	v_mfma_f32_16x16x32_bf16 v[122:125], v[178:181], v[202:205], 0
	v_mfma_f32_16x16x32_bf16 v[110:113], v[160:163], v[210:213], 0
	v_mfma_f32_16x16x32_bf16 v[106:109], v[178:181], v[210:213], 0
	v_mfma_f32_16x16x32_bf16 v[94:97], v[160:163], v[218:221], 0
	v_mfma_f32_16x16x32_bf16 v[90:93], v[178:181], v[218:221], 0
	v_mfma_f32_16x16x32_bf16 v[78:81], v[160:163], v[226:229], 0
	v_mfma_f32_16x16x32_bf16 v[74:77], v[178:181], v[226:229], 0
	v_mfma_f32_16x16x32_bf16 v[126:129], v[164:167], v[206:209], v[126:129]
	v_mfma_f32_16x16x32_bf16 v[122:125], v[182:185], v[206:209], v[122:125]
	v_mfma_f32_16x16x32_bf16 v[110:113], v[164:167], v[214:217], v[110:113]
	v_mfma_f32_16x16x32_bf16 v[106:109], v[182:185], v[214:217], v[106:109]
	v_mfma_f32_16x16x32_bf16 v[94:97], v[164:167], v[222:225], v[94:97]
	v_mfma_f32_16x16x32_bf16 v[90:93], v[182:185], v[222:225], v[90:93]
	v_mfma_f32_16x16x32_bf16 v[78:81], v[164:167], v[230:233], v[78:81]
	v_mfma_f32_16x16x32_bf16 v[74:77], v[182:185], v[230:233], v[74:77]
	v_mfma_f32_16x16x32_bf16 v[118:121], v[186:189], v[202:205], 0
	v_mfma_f32_16x16x32_bf16 v[114:117], v[194:197], v[202:205], 0
	v_mfma_f32_16x16x32_bf16 v[102:105], v[186:189], v[210:213], 0
	v_mfma_f32_16x16x32_bf16 v[98:101], v[194:197], v[210:213], 0
	v_mfma_f32_16x16x32_bf16 v[86:89], v[186:189], v[218:221], 0
	v_mfma_f32_16x16x32_bf16 v[82:85], v[194:197], v[218:221], 0
	v_mfma_f32_16x16x32_bf16 v[70:73], v[186:189], v[226:229], 0
	v_mfma_f32_16x16x32_bf16 v[66:69], v[194:197], v[226:229], 0
	v_mfma_f32_16x16x32_bf16 v[118:121], v[190:193], v[206:209], v[118:121]
	v_mfma_f32_16x16x32_bf16 v[114:117], v[198:201], v[206:209], v[114:117]
	v_mfma_f32_16x16x32_bf16 v[102:105], v[190:193], v[214:217], v[102:105]
	v_mfma_f32_16x16x32_bf16 v[98:101], v[198:201], v[214:217], v[98:101]
	s_setprio 2
	s_barrier
	v_mfma_f32_16x16x32_bf16 v[86:89], v[190:193], v[222:225], v[86:89]
	v_mfma_f32_16x16x32_bf16 v[82:85], v[198:201], v[222:225], v[82:85]
	v_mfma_f32_16x16x32_bf16 v[70:73], v[190:193], v[230:233], v[70:73]
	v_mfma_f32_16x16x32_bf16 v[66:69], v[198:201], v[230:233], v[66:69]
	s_setprio 0
	s_nop 0
	s_add_i32 s72, s60, s33
	s_mov_b32 m0, s72
	ds_read_b128 v[202:205], v176 offset:16384
	ds_read_b128 v[206:209], v176 offset:17408
	ds_read_b128 v[210:213], v176 offset:18432
	ds_read_b128 v[214:217], v176 offset:19456
	ds_read_b128 v[218:221], v176 offset:20480
	ds_read_b128 v[222:225], v176 offset:21504
	ds_read_b128 v[226:229], v176 offset:22528
	ds_read_b128 v[230:233], v176 offset:23552
	global_load_lds_dwordx4 v140, s[44:45]
	s_add_i32 m0, s72, 0x2000
	s_add_u32 s72, s44, 0x40000
	s_addc_u32 s73, s45, 0
	s_add_i32 s74, s61, s33
	global_load_lds_dwordx4 v144, s[44:45]
	s_mov_b32 m0, s74
	s_add_u32 s94, s46, 0x80
	s_addc_u32 s95, s47, 0
	global_load_lds_dwordx4 v140, s[72:73]
	s_add_i32 m0, s74, 0x2000
	s_nop 0
	global_load_lds_dwordx4 v144, s[72:73]
	s_mov_b32 m0, s43
	s_nop 0
	global_load_lds_dwordx4 v138, s[46:47]
	s_mov_b32 m0, s54
	s_nop 0
	global_load_lds_dwordx4 v142, s[46:47]
	s_waitcnt vmcnt(8)
	s_waitcnt lgkmcnt(0)
	s_barrier
	s_setprio 1
	v_mfma_f32_16x16x32_bf16 v[62:65], v[160:163], v[202:205], 0
	v_mfma_f32_16x16x32_bf16 v[58:61], v[178:181], v[202:205], 0
	v_mfma_f32_16x16x32_bf16 v[46:49], v[160:163], v[210:213], 0
	v_mfma_f32_16x16x32_bf16 v[42:45], v[178:181], v[210:213], 0
	v_mfma_f32_16x16x32_bf16 v[30:33], v[160:163], v[218:221], 0
	v_mfma_f32_16x16x32_bf16 v[26:29], v[178:181], v[218:221], 0
	v_mfma_f32_16x16x32_bf16 v[14:17], v[160:163], v[226:229], 0
	v_mfma_f32_16x16x32_bf16 v[10:13], v[178:181], v[226:229], 0
	v_mfma_f32_16x16x32_bf16 v[62:65], v[164:167], v[206:209], v[62:65]
	v_mfma_f32_16x16x32_bf16 v[58:61], v[182:185], v[206:209], v[58:61]
	v_mfma_f32_16x16x32_bf16 v[46:49], v[164:167], v[214:217], v[46:49]
	v_mfma_f32_16x16x32_bf16 v[42:45], v[182:185], v[214:217], v[42:45]
	v_mfma_f32_16x16x32_bf16 v[30:33], v[164:167], v[222:225], v[30:33]
	v_mfma_f32_16x16x32_bf16 v[26:29], v[182:185], v[222:225], v[26:29]
	v_mfma_f32_16x16x32_bf16 v[14:17], v[164:167], v[230:233], v[14:17]
	v_mfma_f32_16x16x32_bf16 v[10:13], v[182:185], v[230:233], v[10:13]
	v_mfma_f32_16x16x32_bf16 v[54:57], v[186:189], v[202:205], 0
	v_mfma_f32_16x16x32_bf16 v[50:53], v[194:197], v[202:205], 0
	v_mfma_f32_16x16x32_bf16 v[38:41], v[186:189], v[210:213], 0
	v_mfma_f32_16x16x32_bf16 v[34:37], v[194:197], v[210:213], 0
	v_mfma_f32_16x16x32_bf16 v[22:25], v[186:189], v[218:221], 0
	v_mfma_f32_16x16x32_bf16 v[18:21], v[194:197], v[218:221], 0
	v_mfma_f32_16x16x32_bf16 v[6:9], v[186:189], v[226:229], 0
	v_mfma_f32_16x16x32_bf16 v[2:5], v[194:197], v[226:229], 0
	v_mfma_f32_16x16x32_bf16 v[54:57], v[190:193], v[206:209], v[54:57]
	v_mfma_f32_16x16x32_bf16 v[50:53], v[198:201], v[206:209], v[50:53]
	v_mfma_f32_16x16x32_bf16 v[38:41], v[190:193], v[214:217], v[38:41]
	v_mfma_f32_16x16x32_bf16 v[34:37], v[198:201], v[214:217], v[34:37]
	s_setprio 2
	s_barrier
	v_mfma_f32_16x16x32_bf16 v[22:25], v[190:193], v[222:225], v[22:25]
	v_mfma_f32_16x16x32_bf16 v[18:21], v[198:201], v[222:225], v[18:21]
	v_mfma_f32_16x16x32_bf16 v[6:9], v[190:193], v[230:233], v[6:9]
	v_mfma_f32_16x16x32_bf16 v[2:5], v[198:201], v[230:233], v[2:5]
	s_setprio 0
	s_nop 0
	s_add_i32 s72, 0, 0x18000
	s_add_i32 s73, 0, 0x1c000
	ds_read_b128 v[160:163], v240 offset:32768
	ds_read_b128 v[164:167], v240 offset:33792
	ds_read_b128 v[178:181], v240 offset:34816
	ds_read_b128 v[182:185], v240 offset:35840
	ds_read_b128 v[186:189], v240 offset:49152
	ds_read_b128 v[190:193], v240 offset:50176
	ds_read_b128 v[194:197], v240 offset:51200
	ds_read_b128 v[198:201], v240 offset:52224
	s_add_u32 s46, s46, 0x40000
	s_addc_u32 s47, s47, 0
	s_mov_b32 m0, s55
	ds_read_b128 v[202:205], v176 offset:32768
	ds_read_b128 v[206:209], v176 offset:33792
	ds_read_b128 v[210:213], v176 offset:34816
	ds_read_b128 v[214:217], v176 offset:35840
	ds_read_b128 v[218:221], v176 offset:36864
	ds_read_b128 v[222:225], v176 offset:37888
	ds_read_b128 v[226:229], v176 offset:38912
	ds_read_b128 v[230:233], v176 offset:39936
	global_load_lds_dwordx4 v138, s[46:47]
	s_mov_b32 m0, s56
	s_nop 0
	global_load_lds_dwordx4 v142, s[46:47]
	s_waitcnt vmcnt(8)
	s_waitcnt lgkmcnt(0)
	s_barrier
	s_setprio 1
	v_mfma_f32_16x16x32_bf16 v[126:129], v[160:163], v[202:205], v[126:129]
	v_mfma_f32_16x16x32_bf16 v[122:125], v[178:181], v[202:205], v[122:125]
	v_mfma_f32_16x16x32_bf16 v[110:113], v[160:163], v[210:213], v[110:113]
	v_mfma_f32_16x16x32_bf16 v[106:109], v[178:181], v[210:213], v[106:109]
	v_mfma_f32_16x16x32_bf16 v[94:97], v[160:163], v[218:221], v[94:97]
	v_mfma_f32_16x16x32_bf16 v[90:93], v[178:181], v[218:221], v[90:93]
	v_mfma_f32_16x16x32_bf16 v[78:81], v[160:163], v[226:229], v[78:81]
	v_mfma_f32_16x16x32_bf16 v[74:77], v[178:181], v[226:229], v[74:77]
	v_mfma_f32_16x16x32_bf16 v[126:129], v[164:167], v[206:209], v[126:129]
	v_mfma_f32_16x16x32_bf16 v[122:125], v[182:185], v[206:209], v[122:125]
	v_mfma_f32_16x16x32_bf16 v[110:113], v[164:167], v[214:217], v[110:113]
	v_mfma_f32_16x16x32_bf16 v[106:109], v[182:185], v[214:217], v[106:109]
	v_mfma_f32_16x16x32_bf16 v[94:97], v[164:167], v[222:225], v[94:97]
	v_mfma_f32_16x16x32_bf16 v[90:93], v[182:185], v[222:225], v[90:93]
	v_mfma_f32_16x16x32_bf16 v[78:81], v[164:167], v[230:233], v[78:81]
	v_mfma_f32_16x16x32_bf16 v[74:77], v[182:185], v[230:233], v[74:77]
	v_mfma_f32_16x16x32_bf16 v[118:121], v[186:189], v[202:205], v[118:121]
	v_mfma_f32_16x16x32_bf16 v[114:117], v[194:197], v[202:205], v[114:117]
	v_mfma_f32_16x16x32_bf16 v[102:105], v[186:189], v[210:213], v[102:105]
	v_mfma_f32_16x16x32_bf16 v[98:101], v[194:197], v[210:213], v[98:101]
	v_mfma_f32_16x16x32_bf16 v[86:89], v[186:189], v[218:221], v[86:89]
	v_mfma_f32_16x16x32_bf16 v[82:85], v[194:197], v[218:221], v[82:85]
	v_mfma_f32_16x16x32_bf16 v[70:73], v[186:189], v[226:229], v[70:73]
	v_mfma_f32_16x16x32_bf16 v[66:69], v[194:197], v[226:229], v[66:69]
	v_mfma_f32_16x16x32_bf16 v[118:121], v[190:193], v[206:209], v[118:121]
	v_mfma_f32_16x16x32_bf16 v[114:117], v[198:201], v[206:209], v[114:117]
	v_mfma_f32_16x16x32_bf16 v[102:105], v[190:193], v[214:217], v[102:105]
	v_mfma_f32_16x16x32_bf16 v[98:101], v[198:201], v[214:217], v[98:101]
	s_setprio 2
	s_barrier
	v_mfma_f32_16x16x32_bf16 v[86:89], v[190:193], v[222:225], v[86:89]
	v_mfma_f32_16x16x32_bf16 v[82:85], v[198:201], v[222:225], v[82:85]
	v_mfma_f32_16x16x32_bf16 v[70:73], v[190:193], v[230:233], v[70:73]
	v_mfma_f32_16x16x32_bf16 v[66:69], v[198:201], v[230:233], v[66:69]
	s_setprio 0
	s_nop 0
	s_add_i32 s46, s72, s33
	s_add_u32 s96, s44, 0x80
	s_addc_u32 s97, s45, 0
	s_mov_b32 m0, s46
	ds_read_b128 v[202:205], v176 offset:49152
	ds_read_b128 v[206:209], v176 offset:50176
	ds_read_b128 v[210:213], v176 offset:51200
	ds_read_b128 v[214:217], v176 offset:52224
	ds_read_b128 v[218:221], v176 offset:53248
	ds_read_b128 v[222:225], v176 offset:54272
	ds_read_b128 v[226:229], v176 offset:55296
	ds_read_b128 v[230:233], v176 offset:56320
	global_load_lds_dwordx4 v140, s[96:97]
	s_add_i32 m0, s46, 0x2000
	s_add_u32 s44, s44, 0x40080
	s_addc_u32 s45, s45, 0
	s_add_i32 s46, s73, s33
	global_load_lds_dwordx4 v144, s[96:97]
	s_mov_b32 m0, s46
	s_nop 0
	global_load_lds_dwordx4 v140, s[44:45]
	s_add_i32 m0, s46, 0x2000
	s_nop 0
	global_load_lds_dwordx4 v144, s[44:45]
	s_mov_b32 m0, s57
	s_nop 0
	global_load_lds_dwordx4 v138, s[94:95]
	s_mov_b32 m0, s58
	s_nop 0
	global_load_lds_dwordx4 v142, s[94:95]
	s_waitcnt vmcnt(8)
	s_waitcnt lgkmcnt(0)
	s_barrier
	s_setprio 1
	v_mfma_f32_16x16x32_bf16 v[62:65], v[160:163], v[202:205], v[62:65]
	v_mfma_f32_16x16x32_bf16 v[58:61], v[178:181], v[202:205], v[58:61]
	v_mfma_f32_16x16x32_bf16 v[46:49], v[160:163], v[210:213], v[46:49]
	v_mfma_f32_16x16x32_bf16 v[42:45], v[178:181], v[210:213], v[42:45]
	v_mfma_f32_16x16x32_bf16 v[30:33], v[160:163], v[218:221], v[30:33]
	v_mfma_f32_16x16x32_bf16 v[26:29], v[178:181], v[218:221], v[26:29]
	v_mfma_f32_16x16x32_bf16 v[14:17], v[160:163], v[226:229], v[14:17]
	v_mfma_f32_16x16x32_bf16 v[10:13], v[178:181], v[226:229], v[10:13]
	v_mfma_f32_16x16x32_bf16 v[62:65], v[164:167], v[206:209], v[62:65]
	v_mfma_f32_16x16x32_bf16 v[58:61], v[182:185], v[206:209], v[58:61]
	v_mfma_f32_16x16x32_bf16 v[46:49], v[164:167], v[214:217], v[46:49]
	v_mfma_f32_16x16x32_bf16 v[42:45], v[182:185], v[214:217], v[42:45]
	v_mfma_f32_16x16x32_bf16 v[30:33], v[164:167], v[222:225], v[30:33]
	v_mfma_f32_16x16x32_bf16 v[26:29], v[182:185], v[222:225], v[26:29]
	v_mfma_f32_16x16x32_bf16 v[14:17], v[164:167], v[230:233], v[14:17]
	v_mfma_f32_16x16x32_bf16 v[10:13], v[182:185], v[230:233], v[10:13]
	v_mfma_f32_16x16x32_bf16 v[54:57], v[186:189], v[202:205], v[54:57]
	v_mfma_f32_16x16x32_bf16 v[50:53], v[194:197], v[202:205], v[50:53]
	v_mfma_f32_16x16x32_bf16 v[38:41], v[186:189], v[210:213], v[38:41]
	v_mfma_f32_16x16x32_bf16 v[34:37], v[194:197], v[210:213], v[34:37]
	v_mfma_f32_16x16x32_bf16 v[22:25], v[186:189], v[218:221], v[22:25]
	v_mfma_f32_16x16x32_bf16 v[18:21], v[194:197], v[218:221], v[18:21]
	v_mfma_f32_16x16x32_bf16 v[6:9], v[186:189], v[226:229], v[6:9]
	v_mfma_f32_16x16x32_bf16 v[2:5], v[194:197], v[226:229], v[2:5]
	v_mfma_f32_16x16x32_bf16 v[54:57], v[190:193], v[206:209], v[54:57]
	v_mfma_f32_16x16x32_bf16 v[50:53], v[198:201], v[206:209], v[50:53]
	v_mfma_f32_16x16x32_bf16 v[38:41], v[190:193], v[214:217], v[38:41]
	v_mfma_f32_16x16x32_bf16 v[34:37], v[198:201], v[214:217], v[34:37]
	s_setprio 2
	s_barrier
	v_mfma_f32_16x16x32_bf16 v[22:25], v[190:193], v[222:225], v[22:25]
	v_mfma_f32_16x16x32_bf16 v[18:21], v[198:201], v[222:225], v[18:21]
	v_mfma_f32_16x16x32_bf16 v[6:9], v[190:193], v[230:233], v[6:9]
	v_mfma_f32_16x16x32_bf16 v[2:5], v[198:201], v[230:233], v[2:5]
	s_setprio 0
	s_nop 0
	s_add_i32 s67, s67, 2
	s_add_u32 s30, s30, 0x100
	s_addc_u32 s31, s31, 0
	s_cmp_gt_u32 s67, 13
	s_cbranch_scc1 .LBB0_181
	s_branch .LBB0_179
.LBB0_178:
	s_waitcnt lgkmcnt(0)
	ds_read_b128 v[160:163], v240
	ds_read_b128 v[164:167], v240 offset:1024
	ds_read_b128 v[178:181], v240 offset:2048
	ds_read_b128 v[182:185], v240 offset:3072
	s_add_u32 s44, s0, s30
	ds_read_b128 v[186:189], v240 offset:16384
	ds_read_b128 v[190:193], v240 offset:17408
	ds_read_b128 v[194:197], v240 offset:18432
	ds_read_b128 v[198:201], v240 offset:19456
	s_addc_u32 s45, s1, s31
	s_add_u32 s44, s44, 0x100
	s_addc_u32 s45, s45, 0
	s_add_u32 s72, s65, s30
	s_addc_u32 s73, s66, s31
	s_cmpk_eq_i32 s30, 0x700
	s_cselect_b32 s47, s29, s45
	s_cselect_b32 s46, s62, s44
	s_cselect_b32 s45, s63, s73
	s_cselect_b32 s44, s64, s72
	s_add_u32 s90, s0, s30
	s_addc_u32 s91, s1, s31
	s_add_i32 m0, s43, 0xc000
	ds_read_b128 v[202:205], v176
	ds_read_b128 v[206:209], v176 offset:1024
	ds_read_b128 v[210:213], v176 offset:2048
	ds_read_b128 v[214:217], v176 offset:3072
	ds_read_b128 v[218:221], v176 offset:4096
	ds_read_b128 v[222:225], v176 offset:5120
	ds_read_b128 v[226:229], v176 offset:6144
	ds_read_b128 v[230:233], v176 offset:7168
	global_load_lds_dwordx4 v148, s[90:91]
	s_add_i32 m0, s43, 0xe000
	s_nop 0
	global_load_lds_dwordx4 v150, s[90:91]
	s_waitcnt vmcnt(8)
	s_waitcnt lgkmcnt(0)
	s_barrier
	s_setprio 1
	v_mfma_f32_16x16x32_bf16 v[126:129], v[160:163], v[202:205], v[126:129]
	v_mfma_f32_16x16x32_bf16 v[122:125], v[178:181], v[202:205], v[122:125]
	v_mfma_f32_16x16x32_bf16 v[110:113], v[160:163], v[210:213], v[110:113]
	v_mfma_f32_16x16x32_bf16 v[106:109], v[178:181], v[210:213], v[106:109]
	v_mfma_f32_16x16x32_bf16 v[94:97], v[160:163], v[218:221], v[94:97]
	v_mfma_f32_16x16x32_bf16 v[90:93], v[178:181], v[218:221], v[90:93]
	v_mfma_f32_16x16x32_bf16 v[78:81], v[160:163], v[226:229], v[78:81]
	v_mfma_f32_16x16x32_bf16 v[74:77], v[178:181], v[226:229], v[74:77]
	v_mfma_f32_16x16x32_bf16 v[126:129], v[164:167], v[206:209], v[126:129]
	v_mfma_f32_16x16x32_bf16 v[122:125], v[182:185], v[206:209], v[122:125]
	v_mfma_f32_16x16x32_bf16 v[110:113], v[164:167], v[214:217], v[110:113]
	v_mfma_f32_16x16x32_bf16 v[106:109], v[182:185], v[214:217], v[106:109]
	v_mfma_f32_16x16x32_bf16 v[94:97], v[164:167], v[222:225], v[94:97]
	v_mfma_f32_16x16x32_bf16 v[90:93], v[182:185], v[222:225], v[90:93]
	v_mfma_f32_16x16x32_bf16 v[78:81], v[164:167], v[230:233], v[78:81]
	v_mfma_f32_16x16x32_bf16 v[74:77], v[182:185], v[230:233], v[74:77]
	v_mfma_f32_16x16x32_bf16 v[118:121], v[186:189], v[202:205], v[118:121]
	v_mfma_f32_16x16x32_bf16 v[114:117], v[194:197], v[202:205], v[114:117]
	v_mfma_f32_16x16x32_bf16 v[102:105], v[186:189], v[210:213], v[102:105]
	v_mfma_f32_16x16x32_bf16 v[98:101], v[194:197], v[210:213], v[98:101]
	v_mfma_f32_16x16x32_bf16 v[86:89], v[186:189], v[218:221], v[86:89]
	v_mfma_f32_16x16x32_bf16 v[82:85], v[194:197], v[218:221], v[82:85]
	v_mfma_f32_16x16x32_bf16 v[70:73], v[186:189], v[226:229], v[70:73]
	v_mfma_f32_16x16x32_bf16 v[66:69], v[194:197], v[226:229], v[66:69]
	v_mfma_f32_16x16x32_bf16 v[118:121], v[190:193], v[206:209], v[118:121]
	v_mfma_f32_16x16x32_bf16 v[114:117], v[198:201], v[206:209], v[114:117]
	v_mfma_f32_16x16x32_bf16 v[102:105], v[190:193], v[214:217], v[102:105]
	v_mfma_f32_16x16x32_bf16 v[98:101], v[198:201], v[214:217], v[98:101]
	s_setprio 2
	s_barrier
	v_mfma_f32_16x16x32_bf16 v[86:89], v[190:193], v[222:225], v[86:89]
	v_mfma_f32_16x16x32_bf16 v[82:85], v[198:201], v[222:225], v[82:85]
	v_mfma_f32_16x16x32_bf16 v[70:73], v[190:193], v[230:233], v[70:73]
	v_mfma_f32_16x16x32_bf16 v[66:69], v[198:201], v[230:233], v[66:69]
	s_setprio 0
	s_nop 0
	s_add_i32 s72, s60, s33
	s_mov_b32 m0, s72
	ds_read_b128 v[202:205], v176 offset:16384
	ds_read_b128 v[206:209], v176 offset:17408
	ds_read_b128 v[210:213], v176 offset:18432
	ds_read_b128 v[214:217], v176 offset:19456
	ds_read_b128 v[218:221], v176 offset:20480
	ds_read_b128 v[222:225], v176 offset:21504
	ds_read_b128 v[226:229], v176 offset:22528
	ds_read_b128 v[230:233], v176 offset:23552
	global_load_lds_dwordx4 v140, s[44:45]
	s_add_i32 m0, s72, 0x2000
	s_add_u32 s72, s44, 0x40000
	s_addc_u32 s73, s45, 0
	s_add_i32 s74, s61, s33
	global_load_lds_dwordx4 v144, s[44:45]
	s_mov_b32 m0, s74
	s_add_u32 s94, s46, 0x80
	s_addc_u32 s95, s47, 0
	global_load_lds_dwordx4 v140, s[72:73]
	s_add_i32 m0, s74, 0x2000
	s_nop 0
	global_load_lds_dwordx4 v144, s[72:73]
	s_mov_b32 m0, s43
	s_nop 0
	global_load_lds_dwordx4 v138, s[46:47]
	s_mov_b32 m0, s54
	s_nop 0
	global_load_lds_dwordx4 v142, s[46:47]
	s_waitcnt vmcnt(8)
	s_waitcnt lgkmcnt(0)
	s_barrier
	s_setprio 1
	v_mfma_f32_16x16x32_bf16 v[62:65], v[160:163], v[202:205], v[62:65]
	v_mfma_f32_16x16x32_bf16 v[58:61], v[178:181], v[202:205], v[58:61]
	v_mfma_f32_16x16x32_bf16 v[46:49], v[160:163], v[210:213], v[46:49]
	v_mfma_f32_16x16x32_bf16 v[42:45], v[178:181], v[210:213], v[42:45]
	v_mfma_f32_16x16x32_bf16 v[30:33], v[160:163], v[218:221], v[30:33]
	v_mfma_f32_16x16x32_bf16 v[26:29], v[178:181], v[218:221], v[26:29]
	v_mfma_f32_16x16x32_bf16 v[14:17], v[160:163], v[226:229], v[14:17]
	v_mfma_f32_16x16x32_bf16 v[10:13], v[178:181], v[226:229], v[10:13]
	v_mfma_f32_16x16x32_bf16 v[62:65], v[164:167], v[206:209], v[62:65]
	v_mfma_f32_16x16x32_bf16 v[58:61], v[182:185], v[206:209], v[58:61]
	v_mfma_f32_16x16x32_bf16 v[46:49], v[164:167], v[214:217], v[46:49]
	v_mfma_f32_16x16x32_bf16 v[42:45], v[182:185], v[214:217], v[42:45]
	v_mfma_f32_16x16x32_bf16 v[30:33], v[164:167], v[222:225], v[30:33]
	v_mfma_f32_16x16x32_bf16 v[26:29], v[182:185], v[222:225], v[26:29]
	v_mfma_f32_16x16x32_bf16 v[14:17], v[164:167], v[230:233], v[14:17]
	v_mfma_f32_16x16x32_bf16 v[10:13], v[182:185], v[230:233], v[10:13]
	v_mfma_f32_16x16x32_bf16 v[54:57], v[186:189], v[202:205], v[54:57]
	v_mfma_f32_16x16x32_bf16 v[50:53], v[194:197], v[202:205], v[50:53]
	v_mfma_f32_16x16x32_bf16 v[38:41], v[186:189], v[210:213], v[38:41]
	v_mfma_f32_16x16x32_bf16 v[34:37], v[194:197], v[210:213], v[34:37]
	v_mfma_f32_16x16x32_bf16 v[22:25], v[186:189], v[218:221], v[22:25]
	v_mfma_f32_16x16x32_bf16 v[18:21], v[194:197], v[218:221], v[18:21]
	v_mfma_f32_16x16x32_bf16 v[6:9], v[186:189], v[226:229], v[6:9]
	v_mfma_f32_16x16x32_bf16 v[2:5], v[194:197], v[226:229], v[2:5]
	v_mfma_f32_16x16x32_bf16 v[54:57], v[190:193], v[206:209], v[54:57]
	v_mfma_f32_16x16x32_bf16 v[50:53], v[198:201], v[206:209], v[50:53]
	v_mfma_f32_16x16x32_bf16 v[38:41], v[190:193], v[214:217], v[38:41]
	v_mfma_f32_16x16x32_bf16 v[34:37], v[198:201], v[214:217], v[34:37]
	s_setprio 2
	s_barrier
	v_mfma_f32_16x16x32_bf16 v[22:25], v[190:193], v[222:225], v[22:25]
	v_mfma_f32_16x16x32_bf16 v[18:21], v[198:201], v[222:225], v[18:21]
	v_mfma_f32_16x16x32_bf16 v[6:9], v[190:193], v[230:233], v[6:9]
	v_mfma_f32_16x16x32_bf16 v[2:5], v[198:201], v[230:233], v[2:5]
	s_setprio 0
	s_nop 0
	s_add_i32 s72, 0, 0x18000
	s_add_i32 s73, 0, 0x1c000
	ds_read_b128 v[160:163], v240 offset:32768
	ds_read_b128 v[164:167], v240 offset:33792
	ds_read_b128 v[178:181], v240 offset:34816
	ds_read_b128 v[182:185], v240 offset:35840
	ds_read_b128 v[186:189], v240 offset:49152
	ds_read_b128 v[190:193], v240 offset:50176
	ds_read_b128 v[194:197], v240 offset:51200
	ds_read_b128 v[198:201], v240 offset:52224
	s_add_u32 s46, s46, 0x40000
	s_addc_u32 s47, s47, 0
	s_mov_b32 m0, s55
	ds_read_b128 v[202:205], v176 offset:32768
	ds_read_b128 v[206:209], v176 offset:33792
	ds_read_b128 v[210:213], v176 offset:34816
	ds_read_b128 v[214:217], v176 offset:35840
	ds_read_b128 v[218:221], v176 offset:36864
	ds_read_b128 v[222:225], v176 offset:37888
	ds_read_b128 v[226:229], v176 offset:38912
	ds_read_b128 v[230:233], v176 offset:39936
	global_load_lds_dwordx4 v138, s[46:47]
	s_mov_b32 m0, s56
	s_nop 0
	global_load_lds_dwordx4 v142, s[46:47]
	s_waitcnt vmcnt(8)
	s_waitcnt lgkmcnt(0)
	s_barrier
	s_setprio 1
	v_mfma_f32_16x16x32_bf16 v[126:129], v[160:163], v[202:205], v[126:129]
	v_mfma_f32_16x16x32_bf16 v[122:125], v[178:181], v[202:205], v[122:125]
	v_mfma_f32_16x16x32_bf16 v[110:113], v[160:163], v[210:213], v[110:113]
	v_mfma_f32_16x16x32_bf16 v[106:109], v[178:181], v[210:213], v[106:109]
	v_mfma_f32_16x16x32_bf16 v[94:97], v[160:163], v[218:221], v[94:97]
	v_mfma_f32_16x16x32_bf16 v[90:93], v[178:181], v[218:221], v[90:93]
	v_mfma_f32_16x16x32_bf16 v[78:81], v[160:163], v[226:229], v[78:81]
	v_mfma_f32_16x16x32_bf16 v[74:77], v[178:181], v[226:229], v[74:77]
	v_mfma_f32_16x16x32_bf16 v[126:129], v[164:167], v[206:209], v[126:129]
	v_mfma_f32_16x16x32_bf16 v[122:125], v[182:185], v[206:209], v[122:125]
	v_mfma_f32_16x16x32_bf16 v[110:113], v[164:167], v[214:217], v[110:113]
	v_mfma_f32_16x16x32_bf16 v[106:109], v[182:185], v[214:217], v[106:109]
	v_mfma_f32_16x16x32_bf16 v[94:97], v[164:167], v[222:225], v[94:97]
	v_mfma_f32_16x16x32_bf16 v[90:93], v[182:185], v[222:225], v[90:93]
	v_mfma_f32_16x16x32_bf16 v[78:81], v[164:167], v[230:233], v[78:81]
	v_mfma_f32_16x16x32_bf16 v[74:77], v[182:185], v[230:233], v[74:77]
	v_mfma_f32_16x16x32_bf16 v[118:121], v[186:189], v[202:205], v[118:121]
	v_mfma_f32_16x16x32_bf16 v[114:117], v[194:197], v[202:205], v[114:117]
	v_mfma_f32_16x16x32_bf16 v[102:105], v[186:189], v[210:213], v[102:105]
	v_mfma_f32_16x16x32_bf16 v[98:101], v[194:197], v[210:213], v[98:101]
	v_mfma_f32_16x16x32_bf16 v[86:89], v[186:189], v[218:221], v[86:89]
	v_mfma_f32_16x16x32_bf16 v[82:85], v[194:197], v[218:221], v[82:85]
	v_mfma_f32_16x16x32_bf16 v[70:73], v[186:189], v[226:229], v[70:73]
	v_mfma_f32_16x16x32_bf16 v[66:69], v[194:197], v[226:229], v[66:69]
	v_mfma_f32_16x16x32_bf16 v[118:121], v[190:193], v[206:209], v[118:121]
	v_mfma_f32_16x16x32_bf16 v[114:117], v[198:201], v[206:209], v[114:117]
	v_mfma_f32_16x16x32_bf16 v[102:105], v[190:193], v[214:217], v[102:105]
	v_mfma_f32_16x16x32_bf16 v[98:101], v[198:201], v[214:217], v[98:101]
	s_setprio 2
	s_barrier
	v_mfma_f32_16x16x32_bf16 v[86:89], v[190:193], v[222:225], v[86:89]
	v_mfma_f32_16x16x32_bf16 v[82:85], v[198:201], v[222:225], v[82:85]
	v_mfma_f32_16x16x32_bf16 v[70:73], v[190:193], v[230:233], v[70:73]
	v_mfma_f32_16x16x32_bf16 v[66:69], v[198:201], v[230:233], v[66:69]
	s_setprio 0
	s_nop 0
	s_add_i32 s46, s72, s33
	s_add_u32 s96, s44, 0x80
	s_addc_u32 s97, s45, 0
	s_mov_b32 m0, s46
	ds_read_b128 v[202:205], v176 offset:49152
	ds_read_b128 v[206:209], v176 offset:50176
	ds_read_b128 v[210:213], v176 offset:51200
	ds_read_b128 v[214:217], v176 offset:52224
	ds_read_b128 v[218:221], v176 offset:53248
	ds_read_b128 v[222:225], v176 offset:54272
	ds_read_b128 v[226:229], v176 offset:55296
	ds_read_b128 v[230:233], v176 offset:56320
	global_load_lds_dwordx4 v140, s[96:97]
	s_add_i32 m0, s46, 0x2000
	s_add_u32 s44, s44, 0x40080
	s_addc_u32 s45, s45, 0
	s_add_i32 s46, s73, s33
	global_load_lds_dwordx4 v144, s[96:97]
	s_mov_b32 m0, s46
	s_nop 0
	global_load_lds_dwordx4 v140, s[44:45]
	s_add_i32 m0, s46, 0x2000
	s_nop 0
	global_load_lds_dwordx4 v144, s[44:45]
	s_mov_b32 m0, s57
	s_nop 0
	global_load_lds_dwordx4 v138, s[94:95]
	s_mov_b32 m0, s58
	s_nop 0
	global_load_lds_dwordx4 v142, s[94:95]
	s_waitcnt vmcnt(8)
	s_waitcnt lgkmcnt(0)
	s_barrier
	s_setprio 1
	v_mfma_f32_16x16x32_bf16 v[62:65], v[160:163], v[202:205], v[62:65]
	v_mfma_f32_16x16x32_bf16 v[58:61], v[178:181], v[202:205], v[58:61]
	v_mfma_f32_16x16x32_bf16 v[46:49], v[160:163], v[210:213], v[46:49]
	v_mfma_f32_16x16x32_bf16 v[42:45], v[178:181], v[210:213], v[42:45]
	v_mfma_f32_16x16x32_bf16 v[30:33], v[160:163], v[218:221], v[30:33]
	v_mfma_f32_16x16x32_bf16 v[26:29], v[178:181], v[218:221], v[26:29]
	v_mfma_f32_16x16x32_bf16 v[14:17], v[160:163], v[226:229], v[14:17]
	v_mfma_f32_16x16x32_bf16 v[10:13], v[178:181], v[226:229], v[10:13]
	v_mfma_f32_16x16x32_bf16 v[62:65], v[164:167], v[206:209], v[62:65]
	v_mfma_f32_16x16x32_bf16 v[58:61], v[182:185], v[206:209], v[58:61]
	v_mfma_f32_16x16x32_bf16 v[46:49], v[164:167], v[214:217], v[46:49]
	v_mfma_f32_16x16x32_bf16 v[42:45], v[182:185], v[214:217], v[42:45]
	v_mfma_f32_16x16x32_bf16 v[30:33], v[164:167], v[222:225], v[30:33]
	v_mfma_f32_16x16x32_bf16 v[26:29], v[182:185], v[222:225], v[26:29]
	v_mfma_f32_16x16x32_bf16 v[14:17], v[164:167], v[230:233], v[14:17]
	v_mfma_f32_16x16x32_bf16 v[10:13], v[182:185], v[230:233], v[10:13]
	v_mfma_f32_16x16x32_bf16 v[54:57], v[186:189], v[202:205], v[54:57]
	v_mfma_f32_16x16x32_bf16 v[50:53], v[194:197], v[202:205], v[50:53]
	v_mfma_f32_16x16x32_bf16 v[38:41], v[186:189], v[210:213], v[38:41]
	v_mfma_f32_16x16x32_bf16 v[34:37], v[194:197], v[210:213], v[34:37]
	v_mfma_f32_16x16x32_bf16 v[22:25], v[186:189], v[218:221], v[22:25]
	v_mfma_f32_16x16x32_bf16 v[18:21], v[194:197], v[218:221], v[18:21]
	v_mfma_f32_16x16x32_bf16 v[6:9], v[186:189], v[226:229], v[6:9]
	v_mfma_f32_16x16x32_bf16 v[2:5], v[194:197], v[226:229], v[2:5]
	v_mfma_f32_16x16x32_bf16 v[54:57], v[190:193], v[206:209], v[54:57]
	v_mfma_f32_16x16x32_bf16 v[50:53], v[198:201], v[206:209], v[50:53]
	v_mfma_f32_16x16x32_bf16 v[38:41], v[190:193], v[214:217], v[38:41]
	v_mfma_f32_16x16x32_bf16 v[34:37], v[198:201], v[214:217], v[34:37]
	s_setprio 2
	s_barrier
	v_mfma_f32_16x16x32_bf16 v[22:25], v[190:193], v[222:225], v[22:25]
	v_mfma_f32_16x16x32_bf16 v[18:21], v[198:201], v[222:225], v[18:21]
	v_mfma_f32_16x16x32_bf16 v[6:9], v[190:193], v[230:233], v[6:9]
	v_mfma_f32_16x16x32_bf16 v[2:5], v[198:201], v[230:233], v[2:5]
	s_setprio 0
	s_nop 0
	s_add_i32 s67, s67, 2
	s_add_u32 s30, s30, 0x100
	s_addc_u32 s31, s31, 0
	s_cmp_gt_u32 s67, 13
	s_cbranch_scc1 .LBB0_181
